# grid barrier: flat release plus the unused per-XCD generation atomic removed from the leader path
# baseline (speedup 1.0000x reference)
.Lgs_133:
	s_or_b64 exec, exec, s[8:9]
	s_mov_b64 s[8:9], exec
	v_mbcnt_lo_u32_b32 v0, s8, 0
	v_mbcnt_hi_u32_b32 v0, s9, v0
	v_cmp_eq_u32_e32 vcc, 0, v0
	s_waitcnt vmcnt(0)
	buffer_inv sc1
	s_and_saveexec_b64 s[10:11], vcc
	s_cbranch_execz .Lgs_135
	s_bcnt1_i32_b64 s8, s[8:9]
	v_mov_b32_e32 v0, s8
	v_readlane_b32 s8, v250, 45
	v_readlane_b32 s9, v250, 46
	s_nop 4
.Lgs_135:
	s_or_b64 exec, exec, s[10:11]
	s_waitcnt vmcnt(0)

.LBB0_133:
	s_or_b64 exec, exec, s[8:9]
	s_mov_b64 s[8:9], exec
	v_mbcnt_lo_u32_b32 v0, s8, 0
	v_mbcnt_hi_u32_b32 v0, s9, v0
	v_cmp_eq_u32_e32 vcc, 0, v0
	s_waitcnt vmcnt(0)
	buffer_inv sc1
	s_and_saveexec_b64 s[10:11], vcc
	s_cbranch_execz .LBB0_135
	s_bcnt1_i32_b64 s8, s[8:9]
	v_mov_b32_e32 v0, s8
	v_readlane_b32 s8, v250, 45
	v_readlane_b32 s9, v250, 46
	s_nop 4
.LBB0_135:
	s_or_b64 exec, exec, s[10:11]
	s_waitcnt vmcnt(0)

.LBB0_201:
	s_or_b64 exec, exec, s[4:5]
	s_mov_b64 s[4:5], exec
	v_mbcnt_lo_u32_b32 v0, s4, 0
	v_mbcnt_hi_u32_b32 v0, s5, v0
	v_cmp_eq_u32_e32 vcc, 0, v0
	s_waitcnt vmcnt(0)
	buffer_inv sc1
	s_and_saveexec_b64 s[8:9], vcc
	s_cbranch_execz .LBB0_203
	s_bcnt1_i32_b64 s4, s[4:5]
	v_mov_b32_e32 v0, s4
	v_readlane_b32 s4, v250, 45
	v_readlane_b32 s5, v250, 46
	s_nop 4
.LBB0_203:
	s_or_b64 exec, exec, s[8:9]
	s_waitcnt vmcnt(0)

.LBB0_277:
	s_or_b64 exec, exec, s[4:5]
	s_mov_b64 s[4:5], exec
	v_mbcnt_lo_u32_b32 v0, s4, 0
	v_mbcnt_hi_u32_b32 v0, s5, v0
	v_cmp_eq_u32_e32 vcc, 0, v0
	s_waitcnt vmcnt(0)
	buffer_inv sc1
	s_and_saveexec_b64 s[6:7], vcc
	s_cbranch_execz .LBB0_279
	s_bcnt1_i32_b64 s4, s[4:5]
	v_mov_b32_e32 v0, s4
	v_readlane_b32 s4, v250, 45
	v_readlane_b32 s5, v250, 46
	s_nop 4
.LBB0_279:
	s_or_b64 exec, exec, s[6:7]
	s_waitcnt vmcnt(0)

.LBB0_349:
	s_or_b64 exec, exec, s[4:5]
	s_mov_b64 s[4:5], exec
	v_mbcnt_lo_u32_b32 v0, s4, 0
	v_mbcnt_hi_u32_b32 v0, s5, v0
	v_cmp_eq_u32_e32 vcc, 0, v0
	s_waitcnt vmcnt(0)
	buffer_inv sc1
	s_and_saveexec_b64 s[6:7], vcc
	s_cbranch_execz .LBB0_351
	s_bcnt1_i32_b64 s4, s[4:5]
	v_mov_b32_e32 v0, s4
	v_readlane_b32 s4, v250, 45
	v_readlane_b32 s5, v250, 46
	s_nop 4
.LBB0_351:
	s_or_b64 exec, exec, s[6:7]
	s_waitcnt vmcnt(0)

.LBB0_417:
	s_or_b64 exec, exec, s[4:5]
	s_mov_b64 s[4:5], exec
	v_mbcnt_lo_u32_b32 v0, s4, 0
	v_mbcnt_hi_u32_b32 v0, s5, v0
	v_cmp_eq_u32_e32 vcc, 0, v0
	s_waitcnt vmcnt(0)
	buffer_inv sc1
	s_and_saveexec_b64 s[6:7], vcc
	s_cbranch_execz .LBB0_419
	s_bcnt1_i32_b64 s4, s[4:5]
	v_mov_b32_e32 v0, s4
	v_readlane_b32 s4, v250, 45
	v_readlane_b32 s5, v250, 46
	s_nop 4
.LBB0_419:
	s_or_b64 exec, exec, s[6:7]
	s_waitcnt vmcnt(0)

.LBB0_797:
	s_or_b64 exec, exec, s[4:5]
	s_mov_b64 s[4:5], exec
	v_mbcnt_lo_u32_b32 v0, s4, 0
	v_mbcnt_hi_u32_b32 v0, s5, v0
	v_cmp_eq_u32_e32 vcc, 0, v0
	s_waitcnt vmcnt(0)
	buffer_inv sc1
	s_and_saveexec_b64 s[6:7], vcc
	s_cbranch_execz .LBB0_799
	s_bcnt1_i32_b64 s4, s[4:5]
	v_mov_b32_e32 v0, s4
	v_readlane_b32 s4, v250, 45
	v_readlane_b32 s5, v250, 46
	s_nop 4
.LBB0_799:
	s_or_b64 exec, exec, s[6:7]
	s_waitcnt vmcnt(0)

.LBB0_895:
	s_or_b64 exec, exec, s[4:5]
	s_mov_b64 s[4:5], exec
	v_mbcnt_lo_u32_b32 v0, s4, 0
	v_mbcnt_hi_u32_b32 v0, s5, v0
	v_cmp_eq_u32_e32 vcc, 0, v0
	s_waitcnt vmcnt(0)
	buffer_inv sc1
	s_and_saveexec_b64 s[6:7], vcc
	s_cbranch_execz .LBB0_897
	s_bcnt1_i32_b64 s4, s[4:5]
	v_mov_b32_e32 v0, s4
	v_readlane_b32 s4, v250, 45
	v_readlane_b32 s5, v250, 46
	s_nop 4
.LBB0_897:
	s_or_b64 exec, exec, s[6:7]
	s_waitcnt vmcnt(0)

.LBB0_954:
	s_or_b64 exec, exec, s[4:5]
	s_mov_b64 s[4:5], exec
	v_mbcnt_lo_u32_b32 v0, s4, 0
	v_mbcnt_hi_u32_b32 v0, s5, v0
	v_cmp_eq_u32_e32 vcc, 0, v0
	s_waitcnt vmcnt(0)
	buffer_inv sc1
	s_and_saveexec_b64 s[6:7], vcc
	s_cbranch_execz .LBB0_956
	s_bcnt1_i32_b64 s4, s[4:5]
	v_mov_b32_e32 v0, s4
	v_readlane_b32 s4, v250, 45
	v_readlane_b32 s5, v250, 46
	s_nop 4
.LBB0_956:
	s_or_b64 exec, exec, s[6:7]
	s_waitcnt vmcnt(0)

.LBB0_1026:
	s_or_b64 exec, exec, s[4:5]
	s_mov_b64 s[4:5], exec
	v_mbcnt_lo_u32_b32 v0, s4, 0
	v_mbcnt_hi_u32_b32 v0, s5, v0
	v_cmp_eq_u32_e32 vcc, 0, v0
	s_waitcnt vmcnt(0)
	buffer_inv sc1
	s_and_saveexec_b64 s[6:7], vcc
	s_cbranch_execz .LBB0_1028
	s_bcnt1_i32_b64 s4, s[4:5]
	v_mov_b32_e32 v0, s4
	v_readlane_b32 s4, v250, 45
	v_readlane_b32 s5, v250, 46
	s_nop 4
.LBB0_1028:
	s_or_b64 exec, exec, s[6:7]
	s_waitcnt vmcnt(0)

.LBB0_1084:
	s_or_b64 exec, exec, s[4:5]
	s_mov_b64 s[4:5], exec
	v_mbcnt_lo_u32_b32 v0, s4, 0
	v_mbcnt_hi_u32_b32 v0, s5, v0
	v_cmp_eq_u32_e32 vcc, 0, v0
	s_waitcnt vmcnt(0)
	buffer_inv sc1
	s_and_saveexec_b64 s[6:7], vcc
	s_cbranch_execz .LBB0_1086
	s_bcnt1_i32_b64 s4, s[4:5]
	v_mov_b32_e32 v0, s4
	v_readlane_b32 s4, v250, 45
	v_readlane_b32 s5, v250, 46
	s_nop 4
.LBB0_1086:
	s_or_b64 exec, exec, s[6:7]
	s_waitcnt vmcnt(0)

.LBB0_1152:
	s_or_b64 exec, exec, s[4:5]
	s_mov_b64 s[4:5], exec
	v_mbcnt_lo_u32_b32 v0, s4, 0
	v_mbcnt_hi_u32_b32 v0, s5, v0
	v_cmp_eq_u32_e32 vcc, 0, v0
	s_waitcnt vmcnt(0)
	buffer_inv sc1
	s_and_saveexec_b64 s[6:7], vcc
	s_cbranch_execz .LBB0_1154
	s_bcnt1_i32_b64 s4, s[4:5]
	v_mov_b32_e32 v0, s4
	v_readlane_b32 s4, v250, 45
	v_readlane_b32 s5, v250, 46
	s_nop 4
.LBB0_1154:
	s_or_b64 exec, exec, s[6:7]
	s_waitcnt vmcnt(0)

.LBB0_1229:
	s_bcnt1_i32_b64 s4, s[4:5]
	v_mov_b32_e32 v0, s4
	v_readlane_b32 s4, v250, 45
	v_readlane_b32 s5, v250, 46
	s_nop 4
	s_getpc_b64 s[98:99]
